# SEAM3: the XCC's first arriver starts the L2 write-back early so the last arriver's write-back is short
# baseline (speedup 1.0000x reference)
; __device__ __forceinline__ unsigned xb_ld(unsigned* p)              { return __hip_atomic_load(p, __ATOMIC_RELAXED, __HIP_MEMORY_SCOPE_AGENT); }
; __device__ __forceinline__ unsigned xb_add(unsigned* p, unsigned v) { return __hip_atomic_fetch_add(p, v, __ATOMIC_RELAXED, __HIP_MEMORY_SCOPE_AGENT); }
; #define XB_SPIN(cond, bar) do { unsigned _sp = 0; while (cond) { __builtin_amdgcn_s_sleep(1); \
;     if ((++_sp & 255u) == 0u) { if (xb_ld(&(bar)[XB_TMO])) break; if (_sp > XB_SPIN_CAP) { atomicAdd(&(bar)[XB_TMO], 1u); break; } } } } while (0)
; __device__ __forceinline__ void xcd_barrier(const XcdBarrier& b) {
;     asm volatile("s_waitcnt vmcnt(0)" ::: "memory");
;     __syncthreads();
;     if (threadIdx.x == 0) {
;         unsigned* bar = b.bar;
;         __builtin_amdgcn_s_waitcnt(0);
;         unsigned nloc = b.st[0], nx = b.st[1];
;         if (nloc == 0u) { xcd_barrier_complete(bar, b.x, nloc, nx); b.st[0] = nloc; b.st[1] = nx; }
;         const unsigned old = xb_add(&bar[XB_XSUB(b.x)], 1u);
;         const unsigned gen = old / nloc;
;         if (old + 1u == (gen + 1u) * nloc) {
;             __builtin_amdgcn_fence(__ATOMIC_RELEASE, "agent");
;             asm volatile("s_waitcnt vmcnt(0)" ::: "memory");
;             const unsigned og = xb_add(&bar[XB_TOP], 1u);
;             const unsigned tg = og / nx;
;             if (og + 1u == (tg + 1u) * nx) xb_add(&bar[XB_TOPGEN], 1u);
;             else XB_SPIN(xb_ld(&bar[XB_TOPGEN]) == tg, bar);
;             __builtin_amdgcn_fence(__ATOMIC_ACQUIRE, "agent");
;             xb_add(&bar[XB_XGEN(b.x)], 1u);
;             asm volatile("s_waitcnt vmcnt(0)" ::: "memory");
.LBB0_350:
	s_cmp_gt_i32 s83, 4
	s_cselect_b64 s[0:1], -1, 0
	s_and_b64 s[4:5], s[4:5], s[0:1]
	s_andn2_b64 vcc, exec, s[4:5]
	s_cbranch_vccnz .LBB0_404
	s_waitcnt vmcnt(0) lgkmcnt(0)
	s_barrier
	s_mov_b64 s[4:5], exec
	v_readlane_b32 s6, v248, 2
	v_readlane_b32 s7, v248, 3
	s_and_b64 s[6:7], s[4:5], s[6:7]
	s_mov_b64 exec, s[6:7]
	s_cbranch_execz .Ls3_other
	s_add_i32 s6, 0, 0x27e00
	v_mov_b32_e32 v0, s6
	ds_read2_b32 v[2:3], v0 offset1:1
	v_readlane_b32 s10, v248, 0
	v_readlane_b32 s11, v248, 1
	s_lshl_b32 s6, s3, 8
	s_nop 1
	s_add_u32 s6, s10, s6
	s_addc_u32 s7, s11, 0
	v_mov_b32_e32 v4, 1
	v_mov_b32_e32 v5, 0x1000
	global_atomic_add v6, v5, v4, s[6:7] offset:1024 sc0
	s_waitcnt vmcnt(0) lgkmcnt(0)
	v_cvt_f32_u32_e32 v7, v2
	v_sub_u32_e32 v8, 0, v2
	v_rcp_iflag_f32_e32 v7, v7
	s_nop 0
	v_mul_f32_e32 v7, 0x4f7ffffe, v7
	v_cvt_u32_f32_e32 v7, v7
	v_mul_lo_u32 v8, v8, v7
	v_mul_hi_u32 v8, v7, v8
	v_add_u32_e32 v7, v7, v8
	v_mul_hi_u32 v7, v6, v7
	v_mul_lo_u32 v8, v7, v2
	v_sub_u32_e32 v8, v6, v8
	v_add_u32_e32 v9, 1, v7
	v_cmp_ge_u32_e32 vcc, v8, v2
	s_nop 1
	v_cndmask_b32_e32 v7, v7, v9, vcc
	v_sub_u32_e32 v9, v8, v2
	v_cndmask_b32_e32 v8, v8, v9, vcc
	v_add_u32_e32 v9, 1, v7
	v_cmp_ge_u32_e32 vcc, v8, v2
	s_nop 1
	v_cndmask_b32_e32 v7, v7, v9, vcc
	v_add_u32_e32 v9, 1, v7
	v_readfirstlane_b32 s98, v7
	v_mul_lo_u32 v13, v7, v2
	v_cmp_eq_u32_e32 vcc, v6, v13
	s_cbranch_vccz .Ls3_nofirst
	buffer_wbl2 sc1
.Ls3_nofirst:
	v_mul_lo_u32 v9, v9, v2
	v_add_u32_e32 v10, 1, v6
	v_cmp_eq_u32_e32 vcc, v10, v9
	s_cbranch_vccz .Ls3_notleader
	buffer_wbl2 sc1
	s_waitcnt vmcnt(0)
	v_mov_b32_e32 v5, 0x2000
	global_atomic_add v5, v4, s[6:7] offset:1024
	v_mov_b32_e32 v5, 0x3000
	global_atomic_add v11, v5, v4, s[10:11] offset:1024 sc0
	v_add_u32_e32 v9, 1, v7
	v_mul_lo_u32 v9, v9, v3
	s_waitcnt vmcnt(0)
	v_add_u32_e32 v10, 1, v11
	v_cmp_eq_u32_e32 vcc, v10, v9
	s_cbranch_vccz .Ls3_notleader
	global_atomic_add v5, v4, s[10:11] offset:1280
